# GEMM unit decode: tile-group height is always 4 (nM=64), runtime float-reciprocal division replaced by shift+mask in all seven GEMM phases
# baseline (speedup 1.0000x reference)
;     __device__ bool next(int i, Unit& u) const { if (!b.next(i >> 1, u)) return false; u.half = i & 1; u.koff = (i & 1) * kbytes; return true; }
;     __device__ bool next(int i, Unit& u) const {
;         const long L = (long)i * G + c; if (L >= nwg) return false;
;         int wgid = (int)L; { const int q = nwg / NXCD, r = nwg % NXCD, xcd = wgid % NXCD, off = wgid / NXCD; wgid = (xcd < r ? xcd * (q + 1) : r * (q + 1) + (xcd - r) * q) + off; }
;         const int nig = WGM * nN, gid = wgid / nig, fm = gid * WGM, gsz = (nM - fm) < WGM ? (nM - fm) : WGM;
;         u.pm = fm + ((wgid % nig) % gsz); u.pn = (wgid % nig) / gsz; u.koff = 0; u.half = 0; return true;
.LBB0_99:
	s_add_i32 s64, s64, 1
	s_mul_i32 s0, s64, s85
	s_mul_hi_u32 s1, s64, s54
	s_add_i32 s1, s1, s0
	s_mul_i32 s0, s64, s54
	s_add_u32 s34, s0, s33
	s_addc_u32 s35, s1, s86
	v_cmp_gt_i64_e32 vcc, s[34:35], v[164:165]
	v_cmp_lt_i64_e64 s[0:1], s[34:35], v[162:163]
	s_cbranch_vccnz .LBB0_101
	s_ashr_i32 s28, s34, 31
	s_lshr_b32 s28, s28, 29
	s_add_i32 s28, s34, s28
	s_ashr_i32 s29, s28, 3
	s_and_b32 s28, s28, -8
	s_sub_i32 s28, s34, s28
	s_cmp_lt_i32 s28, 0
	s_cselect_b32 s30, s3, 0x130
	s_mul_i32 s28, s28, s30
	s_add_i32 s28, s28, s29
	s_mul_hi_i32 s29, s28, 0x6bca1af3
	s_lshr_b32 s30, s29, 31
	s_ashr_i32 s29, s29, 6
	s_add_i32 s29, s29, s30
	s_lshl_b32 s30, s29, 2
	s_mulk_i32 s29, 0x98
	s_sub_i32 s29, s28, s29
	s_lshr_b32 s28, s29, 2
	s_and_b32 s29, s29, 3
	s_add_i32 s30, s30, s29

;     __device__ bool next(int i, Unit& u) const {
;     ...
;         int wgid = (int)L; { const int q = nwg / NXCD, r = nwg % NXCD, xcd = wgid % NXCD, off = wgid / NXCD; wgid = (xcd < r ? xcd * (q + 1) : r * (q + 1) + (xcd - r) * q) + off; }
;         const int nig = WGM * nN, gid = wgid / nig, fm = gid * WGM, gsz = (nM - fm) < WGM ? (nM - fm) : WGM;
;         u.pm = fm + ((wgid % nig) % gsz); u.pn = (wgid % nig) / gsz; u.koff = 0; u.half = 0; return true;
;     __device__ bool next(int i, Unit& u) const { if (!b.next(i >> 1, u)) return false; u.half = i & 1; u.koff = (i & 1) * kbytes; return true; }
.LBB0_509:
	s_ashr_i32 s26, s28, 3
	s_add_i32 s26, s30, s26
	s_ashr_i32 s27, s26, 31
	s_lshr_b32 s27, s27, 27
	s_add_i32 s27, s26, s27
	s_ashr_i32 s28, s27, 5
	s_lshl_b32 s28, s28, 2
	s_andn2_b32 s27, s27, 31
	s_sub_i32 s27, s26, s27
	s_lshr_b32 s26, s27, 2
	s_and_b32 s74, s73, 1
	s_and_b32 s27, s27, 3
	s_add_i32 s28, s28, s27
	s_lshl_b32 s75, s74, 11

;     __device__ bool next(int i, Unit& u) const { if (!b.next(i >> 1, u)) return false; u.half = i & 1; u.koff = (i & 1) * kbytes; return true; }
;     __device__ bool next(int i, Unit& u) const {
;         const long L = (long)i * G + c; if (L >= nwg) return false;
;         int wgid = (int)L; { const int q = nwg / NXCD, r = nwg % NXCD, xcd = wgid % NXCD, off = wgid / NXCD; wgid = (xcd < r ? xcd * (q + 1) : r * (q + 1) + (xcd - r) * q) + off; }
;         const int nig = WGM * nN, gid = wgid / nig, fm = gid * WGM, gsz = (nM - fm) < WGM ? (nM - fm) : WGM;
;         u.pm = fm + ((wgid % nig) % gsz); u.pn = (wgid % nig) / gsz; u.koff = 0; u.half = 0; return true;
.LBB0_618:
	s_ashr_i32 s22, s24, 3
	s_add_i32 s22, s26, s22
	s_ashr_i32 s23, s22, 31
	s_lshr_b32 s23, s23, 27
	s_add_i32 s23, s22, s23
	s_ashr_i32 s24, s23, 5
	s_lshl_b32 s24, s24, 2
	s_andn2_b32 s23, s23, 31
	s_sub_i32 s23, s22, s23
	s_lshr_b32 s22, s23, 2
	s_and_b32 s23, s23, 3
	s_add_i32 s24, s24, s23

;     __device__ bool next(int i, Unit& u) const { if (!b.next(i >> 1, u)) return false; u.half = i & 1; u.koff = (i & 1) * kbytes; return true; }
;     __device__ bool next(int i, Unit& u) const {
;         const long L = (long)i * G + c; if (L >= nwg) return false;
;         int wgid = (int)L; { const int q = nwg / NXCD, r = nwg % NXCD, xcd = wgid % NXCD, off = wgid / NXCD; wgid = (xcd < r ? xcd * (q + 1) : r * (q + 1) + (xcd - r) * q) + off; }
;         const int nig = WGM * nN, gid = wgid / nig, fm = gid * WGM, gsz = (nM - fm) < WGM ? (nM - fm) : WGM;
;         u.pm = fm + ((wgid % nig) % gsz); u.pn = (wgid % nig) / gsz; u.koff = 0; u.half = 0; return true;
.LBB0_760:
	s_add_i32 s43, s43, 1
	s_mul_i32 s4, s43, s85
	s_mul_hi_u32 s5, s43, s54
	s_add_i32 s5, s5, s4
	s_mul_i32 s4, s43, s54
	s_add_u32 s22, s4, s33
	s_addc_u32 s23, s5, s86
	v_cmp_gt_i64_e32 vcc, s[22:23], v[142:143]
	v_cmp_lt_i64_e64 s[4:5], s[22:23], v[140:141]
	s_cbranch_vccnz .LBB0_762
	s_ashr_i32 s18, s22, 31
	s_lshr_b32 s18, s18, 29
	s_add_i32 s18, s22, s18
	s_ashr_i32 s19, s18, 3
	s_and_b32 s18, s18, -8
	s_sub_i32 s18, s22, s18
	s_cmp_lt_i32 s18, 0
	s_cselect_b32 s20, s39, 0x160
	s_mul_i32 s18, s18, s20
	s_add_i32 s18, s18, s19
	s_mul_hi_i32 s19, s18, 0x2e8ba2e9
	s_lshr_b32 s20, s19, 31
	s_ashr_i32 s19, s19, 5
	s_add_i32 s19, s19, s20
	s_lshl_b32 s20, s19, 2
	s_mulk_i32 s19, 0xb0
	s_sub_i32 s19, s18, s19
	s_lshr_b32 s18, s19, 2
	s_and_b32 s19, s19, 3
	s_add_i32 s20, s20, s19

;     __device__ bool next(int i, Unit& u) const { if (!b.next(i >> 1, u)) return false; u.half = i & 1; u.koff = (i & 1) * kbytes; return true; }
;     __device__ bool next(int i, Unit& u) const {
;         const long L = (long)i * G + c; if (L >= nwg) return false;
;         int wgid = (int)L; { const int q = nwg / NXCD, r = nwg % NXCD, xcd = wgid % NXCD, off = wgid / NXCD; wgid = (xcd < r ? xcd * (q + 1) : r * (q + 1) + (xcd - r) * q) + off; }
;         const int nig = WGM * nN, gid = wgid / nig, fm = gid * WGM, gsz = (nM - fm) < WGM ? (nM - fm) : WGM;
;         u.pm = fm + ((wgid % nig) % gsz); u.pn = (wgid % nig) / gsz; u.koff = 0; u.half = 0; return true;
.LBB0_836:
	s_ashr_i32 s4, s24, 3
	s_add_i32 s4, s30, s4
	s_ashr_i32 s5, s4, 31
	s_lshr_b32 s5, s5, 27
	s_add_i32 s5, s4, s5
	s_ashr_i32 s24, s5, 5
	s_lshl_b32 s24, s24, 2
	s_andn2_b32 s5, s5, 31
	s_sub_i32 s4, s4, s5
	s_lshr_b32 s43, s4, 2
	s_and_b32 s4, s4, 3
	s_add_i32 s44, s24, s4

;     __device__ bool next(int i, Unit& u) const { if (!b.next(i >> 1, u)) return false; u.half = i & 1; u.koff = (i & 1) * kbytes; return true; }
;     __device__ bool next(int i, Unit& u) const {
;         const long L = (long)i * G + c; if (L >= nwg) return false;
;         int wgid = (int)L; { const int q = nwg / NXCD, r = nwg % NXCD, xcd = wgid % NXCD, off = wgid / NXCD; wgid = (xcd < r ? xcd * (q + 1) : r * (q + 1) + (xcd - r) * q) + off; }
;         const int nig = WGM * nN, gid = wgid / nig, fm = gid * WGM, gsz = (nM - fm) < WGM ? (nM - fm) : WGM;
;         u.pm = fm + ((wgid % nig) % gsz); u.pn = (wgid % nig) / gsz; u.koff = 0; u.half = 0; return true;
.LBB0_987:
	s_ashr_i32 s30, s34, 3
	s_add_i32 s30, s36, s30
	s_ashr_i32 s31, s30, 31
	s_lshr_b32 s31, s31, 27
	s_add_i32 s31, s30, s31
	s_ashr_i32 s34, s31, 5
	s_lshl_b32 s34, s34, 2
	s_andn2_b32 s31, s31, 31
	s_sub_i32 s31, s30, s31
	s_lshr_b32 s30, s31, 2
	s_and_b32 s31, s31, 3
	s_add_i32 s34, s34, s31

;     __device__ bool next(int i, Unit& u) const { if (!b.next(i >> 1, u)) return false; u.half = i & 1; u.koff = (i & 1) * kbytes; return true; }
;     __device__ bool next(int i, Unit& u) const {
;         const long L = (long)i * G + c; if (L >= nwg) return false;
;         int wgid = (int)L; { const int q = nwg / NXCD, r = nwg % NXCD, xcd = wgid % NXCD, off = wgid / NXCD; wgid = (xcd < r ? xcd * (q + 1) : r * (q + 1) + (xcd - r) * q) + off; }
;         const int nig = WGM * nN, gid = wgid / nig, fm = gid * WGM, gsz = (nM - fm) < WGM ? (nM - fm) : WGM;
;         u.pm = fm + ((wgid % nig) % gsz); u.pn = (wgid % nig) / gsz; u.koff = 0; u.half = 0; return true;
.LBB0_1007:
	s_ashr_i32 s20, s22, 3
	s_add_i32 s20, s24, s20
	s_ashr_i32 s21, s20, 31
	s_lshr_b32 s21, s21, 27
	s_add_i32 s21, s20, s21
	s_ashr_i32 s22, s21, 5
	s_lshl_b32 s22, s22, 2
	s_andn2_b32 s21, s21, 31
	s_sub_i32 s21, s20, s21
	s_lshr_b32 s20, s21, 2
	s_and_b32 s21, s21, 3
	s_add_i32 s22, s22, s21
